# attention fast loops: fold row-sum x+0 init copies, drop launder v_mov copies, xor+add -> precomputed variant add (bit-identical)
# speedup vs baseline: 1.0090x; 1.0055x over previous
.LBB0_916:
	s_cmp_lt_u32 s47, 62
	s_cselect_b32 s44, s40, s21
	s_add_i32 s44, s44, s41
	s_addk_i32 s44, 0xff80
	s_ashr_i32 s45, s44, 31
	s_lshl_b64 s[44:45], s[44:45], 1
	s_add_u32 s44, s39, s44
	s_addc_u32 s45, s67, s45
	s_add_i32 s49, s46, 0xffffc000
	s_and_b32 s49, s49, 0xc000
	s_add_i32 s49, s58, s49
	s_add_i32 m0, s49, 0xc000
	global_load_lds_dwordx4 v196, s[44:45]
	v_lshl_add_u64 v[140:141], s[44:45], 0, v[192:193]
	s_add_i32 m0, s49, 0xc400
	s_add_i32 s44, s48, 1
	global_load_lds_dwordx4 v[140:141], off
	s_cmp_lg_u32 s48, 2
	s_cselect_b32 s48, s44, 0
	s_lshl_b32 s44, s48, 14
	s_and_b32 s49, s46, 0xc000
	s_add_i32 s68, s44, 0
	s_add_i32 s44, s49, 0
	v_add_u32_e32 v156, s44, v206
	ds_read_b128 v[140:143], v156 offset:49152
	ds_read_b128 v[148:151], v156 offset:53248
	ds_read_b128 v[152:155], v156 offset:57344
	ds_read_b128 v[156:159], v156 offset:61440
	s_waitcnt lgkmcnt(0)
	v_mfma_f32_32x32x16_bf16 v[80:95], v[140:143], v[144:147], v[80:95]
	v_xad_u32 v177, v206, 32, s44
	ds_read_b128 v[140:143], v177 offset:49152
	v_mfma_f32_32x32x16_bf16 v[64:79], v[148:151], v[144:147], v[64:79]
	ds_read_b128 v[148:151], v177 offset:53248
	v_mfma_f32_32x32x16_bf16 v[16:31], v[152:155], v[144:147], v[16:31]
	ds_read_b128 v[152:155], v177 offset:57344
	v_mfma_f32_32x32x16_bf16 v[0:15], v[156:159], v[144:147], v[0:15]
	ds_read_b128 v[144:147], v177 offset:61440
	s_waitcnt lgkmcnt(0)
	v_mfma_f32_32x32x16_bf16 v[80:95], v[140:143], v[128:131], v[80:95]
	v_xad_u32 v156, v206, 64, s44
	ds_read_b128 v[140:143], v156 offset:49152
	v_mfma_f32_32x32x16_bf16 v[64:79], v[148:151], v[128:131], v[64:79]
	ds_read_b128 v[148:151], v156 offset:53248
	v_mfma_f32_32x32x16_bf16 v[16:31], v[152:155], v[128:131], v[16:31]
	ds_read_b128 v[152:155], v156 offset:57344
	v_mfma_f32_32x32x16_bf16 v[0:15], v[144:147], v[128:131], v[0:15]
	ds_read_b128 v[128:131], v156 offset:61440
	s_waitcnt lgkmcnt(0)
	v_mfma_f32_32x32x16_bf16 v[80:95], v[140:143], v[132:135], v[80:95]
	v_add_u32_e32 v156, s44, v209
	ds_read_b128 v[140:143], v156 offset:49152
	v_mfma_f32_32x32x16_bf16 v[64:79], v[148:151], v[132:135], v[64:79]
	ds_read_b128 v[144:147], v156 offset:53248
	v_mfma_f32_32x32x16_bf16 v[16:31], v[152:155], v[132:135], v[16:31]
	ds_read_b128 v[148:151], v156 offset:57344
	v_mfma_f32_32x32x16_bf16 v[0:15], v[128:131], v[132:135], v[0:15]
	ds_read_b128 v[128:131], v156 offset:61440
	s_waitcnt lgkmcnt(0)
	v_mfma_f32_32x32x16_bf16 v[80:95], v[140:143], v[136:139], v[80:95]
	v_add_u32_e32 v140, s68, v205
	ds_read_b128 v[132:135], v140
	v_mfma_f32_32x32x16_bf16 v[64:79], v[144:147], v[136:139], v[64:79]
	ds_read_b128 v[140:143], v140 offset:8192
	v_mfma_f32_32x32x16_bf16 v[16:31], v[148:151], v[136:139], v[16:31]
	v_xad_u32 v144, v205, 32, s68
	ds_read_b128 v[176:179], v144
	v_mfma_f32_32x32x16_bf16 v[0:15], v[128:131], v[136:139], v[0:15]
	ds_read_b128 v[182:185], v144 offset:8192
	s_waitcnt lgkmcnt(0)
	v_mfma_f32_32x32x16_bf16 v[144:159], v[132:135], v[160:163], 0
	v_xad_u32 v216, v205, 64, s68
	ds_read_b128 v[186:189], v216
	v_exp_f32_e32 v220, v112
	v_exp_f32_e32 v221, v113
	v_exp_f32_e32 v222, v114
	v_exp_f32_e32 v223, v115
	v_mfma_f32_32x32x16_bf16 v[128:143], v[140:143], v[160:163], 0
	ds_read_b128 v[216:219], v216 offset:8192
	v_exp_f32_e32 v224, v116
	v_exp_f32_e32 v225, v117
	v_exp_f32_e32 v226, v118
	v_exp_f32_e32 v227, v119
	v_mfma_f32_32x32x16_bf16 v[144:159], v[176:179], v[164:167], v[144:159]
	v_add_u32_e32 v181, s68, v213
	ds_read_b128 v[116:119], v181
	v_exp_f32_e32 v228, v120
	v_exp_f32_e32 v229, v121
	v_exp_f32_e32 v230, v122
	v_exp_f32_e32 v231, v123
	v_cvt_pk_bf16_f32 v112, v220, v221
	v_cvt_pk_bf16_f32 v113, v222, v223
	v_cvt_pk_bf16_f32 v114, v224, v225
	v_cvt_pk_bf16_f32 v115, v226, v227
	v_pk_add_f32 v[122:123], v[226:227], v[222:223]
	v_pk_add_f32 v[120:121], v[224:225], v[220:221]
	v_mfma_f32_32x32x16_bf16 v[128:143], v[182:185], v[164:167], v[128:143]
	ds_read_b128 v[176:179], v181 offset:8192
	v_exp_f32_e32 v124, v124
	v_exp_f32_e32 v125, v125
	v_exp_f32_e32 v126, v126
	v_exp_f32_e32 v127, v127
	s_waitcnt lgkmcnt(0)
	v_mfma_f32_32x32x16_bf16 v[144:159], v[186:189], v[168:171], v[144:159]
	v_add_f32_e64 v122, v230, v122
	v_add_f32_e64 v123, v231, v123
	v_add_f32_e64 v120, v228, v120
	v_add_f32_e64 v121, v229, v121
	v_exp_f32_e32 v182, v96
	v_exp_f32_e32 v183, v97
	v_exp_f32_e32 v184, v98
	v_exp_f32_e32 v185, v99
	v_cvt_pk_bf16_f32 v96, v228, v229
	v_cvt_pk_bf16_f32 v97, v230, v231
	v_cvt_pk_bf16_f32 v98, v124, v125
	v_cvt_pk_bf16_f32 v99, v126, v127
	v_pk_add_f32 v[122:123], v[126:127], v[122:123]
	v_pk_add_f32 v[120:121], v[124:125], v[120:121]
	v_mfma_f32_32x32x16_bf16 v[128:143], v[216:219], v[168:171], v[128:143]
	v_exp_f32_e32 v124, v100
	v_exp_f32_e32 v125, v101
	v_exp_f32_e32 v126, v102
	v_exp_f32_e32 v127, v103
	v_mfma_f32_32x32x16_bf16 v[144:159], v[116:119], v[172:175], v[144:159]
	v_exp_f32_e32 v186, v104
	v_exp_f32_e32 v187, v105
	v_exp_f32_e32 v188, v106
	v_exp_f32_e32 v189, v107
	v_pk_add_f32 v[106:107], v[184:185], v[122:123]
	v_pk_add_f32 v[104:105], v[182:183], v[120:121]
	v_cvt_pk_bf16_f32 v100, v182, v183
	v_cvt_pk_bf16_f32 v101, v184, v185
	v_cvt_pk_bf16_f32 v102, v124, v125
	v_cvt_pk_bf16_f32 v103, v126, v127
	v_pk_add_f32 v[118:119], v[126:127], v[106:107]
	v_pk_add_f32 v[116:117], v[124:125], v[104:105]
	v_mfma_f32_32x32x16_bf16 v[128:143], v[176:179], v[172:175], v[128:143]
	v_exp_f32_e32 v120, v108
	v_exp_f32_e32 v121, v109
	v_exp_f32_e32 v122, v110
	v_exp_f32_e32 v123, v111
	v_pk_add_f32 v[110:111], v[188:189], v[118:119]
	v_pk_add_f32 v[108:109], v[186:187], v[116:117]
	v_cvt_pk_bf16_f32 v104, v186, v187
	v_cvt_pk_bf16_f32 v105, v188, v189
	v_cvt_pk_bf16_f32 v106, v120, v121
	v_cvt_pk_bf16_f32 v107, v122, v123
	s_mov_b64 s[44:45], -1
	s_and_b64 vcc, exec, s[42:43]
	v_pk_add_f32 v[178:179], v[122:123], v[110:111]
	v_pk_add_f32 v[176:177], v[120:121], v[108:109]
	s_cbranch_vccz .LBB0_918
	s_waitcnt vmcnt(2) lgkmcnt(0)
	s_mov_b64 s[44:45], 0

.LBB0_924:
	s_add_i32 s2, s46, 0xffff4000
	s_add_i32 s3, s48, 1
	s_cmp_lg_u32 s48, 2
	s_cselect_b32 s48, s3, 0
	s_and_b32 s2, s2, 0xc000
	s_add_i32 s2, s2, 0
	s_lshl_b32 s3, s48, 14
	v_add_u32_e32 v124, s2, v206
	ds_read_b128 v[108:111], v124 offset:49152
	ds_read_b128 v[116:119], v124 offset:53248
	ds_read_b128 v[120:123], v124 offset:57344
	ds_read_b128 v[124:127], v124 offset:61440
	s_waitcnt lgkmcnt(0)
	v_mfma_f32_32x32x16_bf16 v[80:95], v[108:111], v[112:115], v[80:95]
	v_xad_u32 v182, v206, 32, s2
	ds_read_b128 v[108:111], v182 offset:49152
	s_add_i32 s3, s3, 0
	v_mfma_f32_32x32x16_bf16 v[64:79], v[116:119], v[112:115], v[64:79]
	ds_read_b128 v[116:119], v182 offset:53248
	v_mfma_f32_32x32x16_bf16 v[16:31], v[120:123], v[112:115], v[16:31]
	ds_read_b128 v[120:123], v182 offset:57344
	v_mfma_f32_32x32x16_bf16 v[0:15], v[124:127], v[112:115], v[0:15]
	ds_read_b128 v[112:115], v182 offset:61440
	s_waitcnt lgkmcnt(0)
	v_mfma_f32_32x32x16_bf16 v[80:95], v[108:111], v[96:99], v[80:95]
	v_xad_u32 v124, v206, 64, s2
	ds_read_b128 v[108:111], v124 offset:49152
	v_mfma_f32_32x32x16_bf16 v[64:79], v[116:119], v[96:99], v[64:79]
	ds_read_b128 v[116:119], v124 offset:53248
	v_mfma_f32_32x32x16_bf16 v[16:31], v[120:123], v[96:99], v[16:31]
	ds_read_b128 v[120:123], v124 offset:57344
	v_mfma_f32_32x32x16_bf16 v[0:15], v[112:115], v[96:99], v[0:15]
	ds_read_b128 v[96:99], v124 offset:61440
	s_waitcnt lgkmcnt(0)
	v_mfma_f32_32x32x16_bf16 v[80:95], v[108:111], v[100:103], v[80:95]
	v_add_u32_e32 v124, s2, v209
	ds_read_b128 v[108:111], v124 offset:49152
	v_mfma_f32_32x32x16_bf16 v[64:79], v[116:119], v[100:103], v[64:79]
	ds_read_b128 v[112:115], v124 offset:53248
	v_mfma_f32_32x32x16_bf16 v[16:31], v[120:123], v[100:103], v[16:31]
	ds_read_b128 v[116:119], v124 offset:57344
	v_mfma_f32_32x32x16_bf16 v[0:15], v[96:99], v[100:103], v[0:15]
	ds_read_b128 v[120:123], v124 offset:61440
	s_waitcnt lgkmcnt(0)
	v_mfma_f32_32x32x16_bf16 v[80:95], v[108:111], v[104:107], v[80:95]
	v_add_u32_e32 v100, s3, v205
	ds_read_b128 v[96:99], v100
	v_mfma_f32_32x32x16_bf16 v[64:79], v[112:115], v[104:107], v[64:79]
	ds_read_b128 v[100:103], v100 offset:8192
	v_mfma_f32_32x32x16_bf16 v[16:31], v[116:119], v[104:107], v[16:31]
	v_xad_u32 v108, v205, 32, s3
	ds_read_b128 v[182:185], v108
	v_mfma_f32_32x32x16_bf16 v[0:15], v[120:123], v[104:107], v[0:15]
	ds_read_b128 v[186:189], v108 offset:8192
	s_waitcnt lgkmcnt(0)
	v_mfma_f32_32x32x16_bf16 v[112:127], v[96:99], v[160:163], 0
	v_xad_u32 v104, v205, 64, s3
	ds_read_b128 v[216:219], v104
	v_exp_f32_e32 v224, v144
	v_exp_f32_e32 v225, v145
	v_exp_f32_e32 v226, v146
	v_exp_f32_e32 v227, v147
	ds_read_b128 v[220:223], v104 offset:8192
	v_mfma_f32_32x32x16_bf16 v[96:111], v[100:103], v[160:163], 0
	v_exp_f32_e32 v228, v148
	v_exp_f32_e32 v229, v149
	v_exp_f32_e32 v230, v150
	v_exp_f32_e32 v231, v151
	v_mfma_f32_32x32x16_bf16 v[112:127], v[182:185], v[164:167], v[112:127]
	v_add_u32_e32 v181, s3, v213
	ds_read_b128 v[148:151], v181
	v_exp_f32_e32 v232, v152
	v_exp_f32_e32 v233, v153
	v_exp_f32_e32 v234, v154
	v_exp_f32_e32 v235, v155
	v_cvt_pk_bf16_f32 v144, v224, v225
	v_cvt_pk_bf16_f32 v145, v226, v227
	v_cvt_pk_bf16_f32 v146, v228, v229
	v_cvt_pk_bf16_f32 v147, v230, v231
	v_pk_add_f32 v[154:155], v[230:231], v[226:227]
	v_pk_add_f32 v[152:153], v[228:229], v[224:225]
	v_mfma_f32_32x32x16_bf16 v[96:111], v[186:189], v[164:167], v[96:111]
	ds_read_b128 v[182:185], v181 offset:8192
	v_exp_f32_e32 v156, v156
	v_exp_f32_e32 v157, v157
	v_exp_f32_e32 v158, v158
	v_exp_f32_e32 v159, v159
	s_waitcnt lgkmcnt(0)
	v_mfma_f32_32x32x16_bf16 v[112:127], v[216:219], v[168:171], v[112:127]
	v_add_f32_e64 v154, v234, v154
	v_add_f32_e64 v155, v235, v155
	v_add_f32_e64 v152, v232, v152
	v_add_f32_e64 v153, v233, v153
	v_exp_f32_e32 v186, v128
	v_exp_f32_e32 v187, v129
	v_exp_f32_e32 v188, v130
	v_exp_f32_e32 v189, v131
	v_cvt_pk_bf16_f32 v128, v232, v233
	v_cvt_pk_bf16_f32 v129, v234, v235
	v_cvt_pk_bf16_f32 v130, v156, v157
	v_cvt_pk_bf16_f32 v131, v158, v159
	v_pk_add_f32 v[154:155], v[158:159], v[154:155]
	v_pk_add_f32 v[152:153], v[156:157], v[152:153]
	v_mfma_f32_32x32x16_bf16 v[96:111], v[220:223], v[168:171], v[96:111]
	v_exp_f32_e32 v156, v132
	v_exp_f32_e32 v157, v133
	v_exp_f32_e32 v158, v134
	v_exp_f32_e32 v159, v135
	v_mfma_f32_32x32x16_bf16 v[112:127], v[148:151], v[172:175], v[112:127]
	v_exp_f32_e32 v216, v136
	v_exp_f32_e32 v217, v137
	v_exp_f32_e32 v218, v138
	v_exp_f32_e32 v219, v139
	v_pk_add_f32 v[138:139], v[188:189], v[154:155]
	v_pk_add_f32 v[136:137], v[186:187], v[152:153]
	v_cvt_pk_bf16_f32 v132, v186, v187
	v_cvt_pk_bf16_f32 v133, v188, v189
	v_cvt_pk_bf16_f32 v134, v156, v157
	v_cvt_pk_bf16_f32 v135, v158, v159
	v_pk_add_f32 v[150:151], v[158:159], v[138:139]
	v_pk_add_f32 v[148:149], v[156:157], v[136:137]
	v_mfma_f32_32x32x16_bf16 v[96:111], v[182:185], v[172:175], v[96:111]
	v_exp_f32_e32 v152, v140
	v_exp_f32_e32 v153, v141
	v_exp_f32_e32 v154, v142
	v_exp_f32_e32 v155, v143
	v_pk_add_f32 v[142:143], v[218:219], v[150:151]
	v_pk_add_f32 v[140:141], v[216:217], v[148:149]
	v_cvt_pk_bf16_f32 v136, v216, v217
	v_cvt_pk_bf16_f32 v137, v218, v219
	v_cvt_pk_bf16_f32 v138, v152, v153
	v_cvt_pk_bf16_f32 v139, v154, v155
	s_mov_b64 s[2:3], -1
	s_and_b64 vcc, exec, s[44:45]
	v_pk_add_f32 v[142:143], v[154:155], v[142:143]
	v_pk_add_f32 v[140:141], v[152:153], v[140:141]
	s_cbranch_vccz .LBB0_930
	s_and_b64 vcc, exec, s[42:43]
	s_cbranch_vccz .LBB0_927
	s_waitcnt vmcnt(0) lgkmcnt(0)
	s_mov_b64 s[2:3], 0

.LBB0_940:
	s_add_i32 s46, s41, 1
	s_cmp_lg_u32 s41, 2
	s_cselect_b32 s41, s46, 0
	s_lshl_b32 s46, s41, 14
	s_add_i32 s49, s46, 0
	s_add_i32 s46, s20, 0xffff4000
	v_add_u32_e32 v100, s49, v205
	ds_read_b128 v[96:99], v100
	ds_read_b128 v[100:103], v100 offset:8192
	s_waitcnt lgkmcnt(0)
	v_mfma_f32_32x32x16_bf16 v[112:127], v[96:99], v[160:163], 0
	v_xad_u32 v104, v205, 32, s49
	ds_read_b128 v[128:131], v104
	ds_read_b128 v[132:135], v104 offset:8192
	v_xad_u32 v96, v205, 64, s49
	ds_read_b128 v[136:139], v96
	s_and_b32 s46, s46, 0x8000
	s_add_i32 s48, s46, 0
	v_exp_f32_e32 v140, v48
	v_exp_f32_e32 v141, v49
	v_exp_f32_e32 v142, v50
	v_exp_f32_e32 v143, v51
	ds_read_b128 v[48:51], v96 offset:8192
	v_mfma_f32_32x32x16_bf16 v[96:111], v[100:103], v[160:163], 0
	v_exp_f32_e32 v144, v52
	v_exp_f32_e32 v145, v53
	v_exp_f32_e32 v146, v54
	v_exp_f32_e32 v147, v55
	s_waitcnt lgkmcnt(0)
	v_mfma_f32_32x32x16_bf16 v[112:127], v[128:131], v[164:167], v[112:127]
	v_add_u32_e32 v152, s49, v213
	ds_read_b128 v[52:55], v152
	v_exp_f32_e32 v148, v56
	v_exp_f32_e32 v149, v57
	v_exp_f32_e32 v150, v58
	v_exp_f32_e32 v151, v59
	v_mfma_f32_32x32x16_bf16 v[96:111], v[132:135], v[164:167], v[96:111]
	ds_read_b128 v[56:59], v152 offset:8192
	v_exp_f32_e32 v128, v60
	v_exp_f32_e32 v129, v61
	v_exp_f32_e32 v130, v62
	v_exp_f32_e32 v131, v63
	v_mfma_f32_32x32x16_bf16 v[112:127], v[136:139], v[168:171], v[112:127]
	v_add_u32_e32 v156, s48, v206
	ds_read_b128 v[60:63], v156 offset:49152
	v_exp_f32_e32 v132, v32
	v_exp_f32_e32 v133, v33
	v_exp_f32_e32 v134, v34
	v_exp_f32_e32 v135, v35
	v_mfma_f32_32x32x16_bf16 v[96:111], v[48:51], v[168:171], v[96:111]
	ds_read_b128 v[32:35], v156 offset:53248
	v_exp_f32_e32 v136, v36
	v_exp_f32_e32 v137, v37
	v_exp_f32_e32 v138, v38
	v_exp_f32_e32 v139, v39
	s_waitcnt lgkmcnt(0)
	v_mfma_f32_32x32x16_bf16 v[112:127], v[52:55], v[172:175], v[112:127]
	ds_read_b128 v[36:39], v156 offset:57344
	v_exp_f32_e32 v152, v40
	v_exp_f32_e32 v153, v41
	v_exp_f32_e32 v154, v42
	v_exp_f32_e32 v155, v43
	v_mfma_f32_32x32x16_bf16 v[96:111], v[56:59], v[172:175], v[96:111]
	ds_read_b128 v[40:43], v156 offset:61440
	v_exp_f32_e32 v156, v44
	v_exp_f32_e32 v157, v45
	v_exp_f32_e32 v158, v46
	v_exp_f32_e32 v159, v47
	v_cvt_pk_bf16_f32 v44, v140, v141
	v_cvt_pk_bf16_f32 v45, v142, v143
	v_cvt_pk_bf16_f32 v46, v144, v145
	v_cvt_pk_bf16_f32 v47, v146, v147
	s_nop 1
	v_mfma_f32_32x32x16_bf16 v[80:95], v[60:63], v[44:47], v[80:95]
	v_xad_u32 v178, v206, 32, s48
	ds_read_b128 v[48:51], v178 offset:49152
	v_cvt_pk_bf16_f32 v52, v148, v149
	v_cvt_pk_bf16_f32 v53, v150, v151
	v_cvt_pk_bf16_f32 v54, v128, v129
	v_cvt_pk_bf16_f32 v55, v130, v131
	v_mfma_f32_32x32x16_bf16 v[64:79], v[32:35], v[44:47], v[64:79]
	ds_read_b128 v[56:59], v178 offset:53248
	v_pk_add_f32 v[62:63], v[146:147], v[142:143]
	v_pk_add_f32 v[60:61], v[144:145], v[140:141]
	s_waitcnt lgkmcnt(0)
	v_mfma_f32_32x32x16_bf16 v[16:31], v[36:39], v[44:47], v[16:31]
	ds_read_b128 v[32:35], v178 offset:57344
	v_add_f32_e64 v62, v150, v62
	v_add_f32_e64 v63, v151, v63
	v_add_f32_e64 v60, v148, v60
	v_add_f32_e64 v61, v149, v61
	v_pk_add_f32 v[62:63], v[130:131], v[62:63]
	v_pk_add_f32 v[60:61], v[128:129], v[60:61]
	v_mfma_f32_32x32x16_bf16 v[0:15], v[40:43], v[44:47], v[0:15]
	ds_read_b128 v[36:39], v178 offset:61440
	v_mfma_f32_32x32x16_bf16 v[80:95], v[48:51], v[52:55], v[80:95]
	v_xad_u32 v140, v206, 64, s48
	ds_read_b128 v[40:43], v140 offset:49152
	v_cvt_pk_bf16_f32 v44, v132, v133
	v_cvt_pk_bf16_f32 v45, v134, v135
	v_cvt_pk_bf16_f32 v46, v136, v137
	v_cvt_pk_bf16_f32 v47, v138, v139
	v_mfma_f32_32x32x16_bf16 v[64:79], v[56:59], v[52:55], v[64:79]
	ds_read_b128 v[48:51], v140 offset:53248
	v_add_f32_e64 v62, v134, v62
	v_add_f32_e64 v63, v135, v63
	v_add_f32_e64 v60, v132, v60
	v_add_f32_e64 v61, v133, v61
	v_pk_add_f32 v[62:63], v[138:139], v[62:63]
	v_pk_add_f32 v[60:61], v[136:137], v[60:61]
	s_waitcnt lgkmcnt(0)
	v_mfma_f32_32x32x16_bf16 v[16:31], v[32:35], v[52:55], v[16:31]
	ds_read_b128 v[56:59], v140 offset:57344
	v_add_f32_e64 v62, v154, v62
	v_add_f32_e64 v63, v155, v63
	v_add_f32_e64 v60, v152, v60
	v_add_f32_e64 v61, v153, v61
	v_pk_add_f32 v[130:131], v[158:159], v[62:63]
	v_pk_add_f32 v[128:129], v[156:157], v[60:61]
	v_mfma_f32_32x32x16_bf16 v[0:15], v[36:39], v[52:55], v[0:15]
	ds_read_b128 v[32:35], v140 offset:61440
	v_mfma_f32_32x32x16_bf16 v[80:95], v[40:43], v[44:47], v[80:95]
	v_add_u32_e32 v60, s48, v209
	ds_read_b128 v[36:39], v60 offset:49152
	v_cvt_pk_bf16_f32 v52, v152, v153
	v_cvt_pk_bf16_f32 v53, v154, v155
	v_cvt_pk_bf16_f32 v54, v156, v157
	v_cvt_pk_bf16_f32 v55, v158, v159
	v_mfma_f32_32x32x16_bf16 v[64:79], v[48:51], v[44:47], v[64:79]
	ds_read_b128 v[40:43], v60 offset:53248
	s_waitcnt lgkmcnt(0)
	v_mfma_f32_32x32x16_bf16 v[16:31], v[56:59], v[44:47], v[16:31]
	ds_read_b128 v[48:51], v60 offset:57344
	v_mfma_f32_32x32x16_bf16 v[0:15], v[32:35], v[44:47], v[0:15]
	ds_read_b128 v[56:59], v60 offset:61440
	v_mfma_f32_32x32x16_bf16 v[80:95], v[36:39], v[52:55], v[80:95]
	v_mfma_f32_32x32x16_bf16 v[64:79], v[40:43], v[52:55], v[64:79]
	s_waitcnt lgkmcnt(0)
	v_mfma_f32_32x32x16_bf16 v[16:31], v[48:51], v[52:55], v[16:31]
	v_mfma_f32_32x32x16_bf16 v[0:15], v[56:59], v[52:55], v[0:15]
	s_mov_b64 s[46:47], -1
	s_and_b64 vcc, exec, s[42:43]
	s_cbranch_vccz .LBB0_946
	s_and_b64 vcc, exec, s[2:3]
	s_cbranch_vccz .LBB0_943
	s_waitcnt vmcnt(0) lgkmcnt(0)
	s_mov_b64 s[46:47], 0

.LBB0_952:
	s_add_i32 s48, s48, 0xc000
	s_add_i32 s44, s41, 1
	s_cmp_lg_u32 s41, 2
	s_cselect_b32 s41, s44, 0
	s_lshl_b32 s44, s41, 14
	s_add_i32 s44, s44, 0
	v_exp_f32_e32 v144, v112
	v_add_u32_e32 v36, s44, v205
	ds_read_b128 v[32:35], v36
	ds_read_b128 v[36:39], v36 offset:8192
	s_waitcnt lgkmcnt(0)
	v_mfma_f32_32x32x16_bf16 v[48:63], v[32:35], v[160:163], 0
	v_xad_u32 v40, v205, 32, s44
	ds_read_b128 v[132:135], v40
	ds_read_b128 v[136:139], v40 offset:8192
	v_xad_u32 v32, v205, 64, s44
	ds_read_b128 v[140:143], v32
	v_exp_f32_e32 v145, v113
	v_exp_f32_e32 v146, v114
	v_exp_f32_e32 v147, v115
	ds_read_b128 v[112:115], v32 offset:8192
	v_mfma_f32_32x32x16_bf16 v[32:47], v[36:39], v[160:163], 0
	v_exp_f32_e32 v148, v116
	v_exp_f32_e32 v149, v117
	v_exp_f32_e32 v150, v118
	v_exp_f32_e32 v151, v119
	s_waitcnt lgkmcnt(0)
	v_mfma_f32_32x32x16_bf16 v[48:63], v[132:135], v[164:167], v[48:63]
	v_add_u32_e32 v156, s44, v213
	ds_read_b128 v[116:119], v156
	v_exp_f32_e32 v152, v120
	v_exp_f32_e32 v153, v121
	v_exp_f32_e32 v154, v122
	v_exp_f32_e32 v155, v123
	v_mfma_f32_32x32x16_bf16 v[32:47], v[136:139], v[164:167], v[32:47]
	ds_read_b128 v[120:123], v156 offset:8192
	v_exp_f32_e32 v156, v124
	v_exp_f32_e32 v157, v125
	v_exp_f32_e32 v158, v126
	v_exp_f32_e32 v159, v127
	v_mfma_f32_32x32x16_bf16 v[48:63], v[140:143], v[168:171], v[48:63]
	v_add_u32_e32 v132, s48, v206
	ds_read_b128 v[124:127], v132 offset:16384
	v_exp_f32_e32 v136, v96
	v_exp_f32_e32 v137, v97
	v_exp_f32_e32 v138, v98
	v_exp_f32_e32 v139, v99
	v_mfma_f32_32x32x16_bf16 v[32:47], v[112:115], v[168:171], v[32:47]
	ds_read_b128 v[96:99], v132 offset:20480
	v_exp_f32_e32 v140, v100
	v_exp_f32_e32 v141, v101
	v_exp_f32_e32 v142, v102
	v_exp_f32_e32 v143, v103
	s_waitcnt lgkmcnt(0)
	v_mfma_f32_32x32x16_bf16 v[48:63], v[116:119], v[172:175], v[48:63]
	ds_read_b128 v[100:103], v132 offset:24576
	v_exp_f32_e32 v178, v104
	v_exp_f32_e32 v179, v105
	v_exp_f32_e32 v180, v106
	v_exp_f32_e32 v181, v107
	v_mfma_f32_32x32x16_bf16 v[32:47], v[120:123], v[172:175], v[32:47]
	ds_read_b128 v[104:107], v132 offset:28672
	v_exp_f32_e32 v182, v108
	v_exp_f32_e32 v183, v109
	v_exp_f32_e32 v184, v110
	v_exp_f32_e32 v185, v111
	v_cvt_pk_bf16_f32 v108, v144, v145
	v_cvt_pk_bf16_f32 v109, v146, v147
	v_cvt_pk_bf16_f32 v110, v148, v149
	v_cvt_pk_bf16_f32 v111, v150, v151
	s_nop 1
	v_mfma_f32_32x32x16_bf16 v[80:95], v[124:127], v[108:111], v[80:95]
	v_xad_u32 v186, v206, 32, s48
	ds_read_b128 v[112:115], v186 offset:16384
	v_cvt_pk_bf16_f32 v116, v152, v153
	v_cvt_pk_bf16_f32 v117, v154, v155
	v_cvt_pk_bf16_f32 v118, v156, v157
	v_cvt_pk_bf16_f32 v119, v158, v159
	v_mfma_f32_32x32x16_bf16 v[64:79], v[96:99], v[108:111], v[64:79]
	ds_read_b128 v[120:123], v186 offset:20480
	v_pk_add_f32 v[126:127], v[150:151], v[146:147]
	v_pk_add_f32 v[124:125], v[148:149], v[144:145]
	s_waitcnt lgkmcnt(0)
	v_mfma_f32_32x32x16_bf16 v[16:31], v[100:103], v[108:111], v[16:31]
	ds_read_b128 v[132:135], v186 offset:24576
	v_add_f32_e64 v98, v154, v126
	v_add_f32_e64 v99, v155, v127
	v_add_f32_e64 v96, v152, v124
	v_add_f32_e64 v97, v153, v125
	v_pk_add_f32 v[98:99], v[158:159], v[98:99]
	v_pk_add_f32 v[96:97], v[156:157], v[96:97]
	v_mfma_f32_32x32x16_bf16 v[0:15], v[104:107], v[108:111], v[0:15]
	ds_read_b128 v[100:103], v186 offset:28672
	v_mfma_f32_32x32x16_bf16 v[80:95], v[112:115], v[116:119], v[80:95]
	v_xad_u32 v124, v206, 64, s48
	ds_read_b128 v[104:107], v124 offset:16384
	v_cvt_pk_bf16_f32 v108, v136, v137
	v_cvt_pk_bf16_f32 v109, v138, v139
	v_cvt_pk_bf16_f32 v110, v140, v141
	v_cvt_pk_bf16_f32 v111, v142, v143
	v_mfma_f32_32x32x16_bf16 v[64:79], v[120:123], v[116:119], v[64:79]
	ds_read_b128 v[112:115], v124 offset:20480
	v_add_f32_e64 v98, v138, v98
	v_add_f32_e64 v99, v139, v99
	v_add_f32_e64 v96, v136, v96
	v_add_f32_e64 v97, v137, v97
	v_pk_add_f32 v[98:99], v[142:143], v[98:99]
	v_pk_add_f32 v[96:97], v[140:141], v[96:97]
	s_waitcnt lgkmcnt(0)
	v_mfma_f32_32x32x16_bf16 v[16:31], v[132:135], v[116:119], v[16:31]
	ds_read_b128 v[120:123], v124 offset:24576
	v_add_f32_e64 v98, v180, v98
	v_add_f32_e64 v99, v181, v99
	v_add_f32_e64 v96, v178, v96
	v_add_f32_e64 v97, v179, v97
	v_pk_add_f32 v[98:99], v[184:185], v[98:99]
	v_pk_add_f32 v[96:97], v[182:183], v[96:97]
	v_mfma_f32_32x32x16_bf16 v[0:15], v[100:103], v[116:119], v[0:15]
	ds_read_b128 v[124:127], v124 offset:28672
	v_mfma_f32_32x32x16_bf16 v[80:95], v[104:107], v[108:111], v[80:95]
	v_add_u32_e32 v132, s48, v209
	ds_read_b128 v[100:103], v132 offset:16384
	v_cvt_pk_bf16_f32 v116, v178, v179
	v_cvt_pk_bf16_f32 v117, v180, v181
	v_cvt_pk_bf16_f32 v118, v182, v183
	v_cvt_pk_bf16_f32 v119, v184, v185
	v_mfma_f32_32x32x16_bf16 v[64:79], v[112:115], v[108:111], v[64:79]
	ds_read_b128 v[104:107], v132 offset:20480
	s_waitcnt lgkmcnt(0)
	v_mfma_f32_32x32x16_bf16 v[16:31], v[120:123], v[108:111], v[16:31]
	ds_read_b128 v[112:115], v132 offset:24576
	v_mfma_f32_32x32x16_bf16 v[0:15], v[124:127], v[108:111], v[0:15]
	ds_read_b128 v[120:123], v132 offset:28672
	v_mfma_f32_32x32x16_bf16 v[80:95], v[100:103], v[116:119], v[80:95]
	v_mfma_f32_32x32x16_bf16 v[64:79], v[104:107], v[116:119], v[64:79]
	s_waitcnt lgkmcnt(0)
	v_mfma_f32_32x32x16_bf16 v[16:31], v[112:115], v[116:119], v[16:31]
	v_mfma_f32_32x32x16_bf16 v[0:15], v[120:123], v[116:119], v[0:15]
	s_mov_b64 s[44:45], -1
	s_and_b64 vcc, exec, s[46:47]
	s_cbranch_vccz .LBB0_958
	s_and_b64 vcc, exec, s[42:43]
	s_cbranch_vccz .LBB0_955
	s_waitcnt vmcnt(0) lgkmcnt(0)
	s_mov_b64 s[44:45], 0
